# v30 + gate/up epilogue (prompt units): conv weight/bias pointer load at the epilogue start and the eight weight loads issued before the halo exchange and its barrier
# baseline (speedup 1.0000x reference)
;     __device__ __forceinline__ void operator()(const f32x4 (&acc)[2][2][4][2], const Unit& u, int wr, int wc, int fr, int fq) const {
;         const int colt = u.pn * 128 + 32 * wc + 8 * fq;
;         const int row0 = u.pm * BM + wr * 64 + fr;
;         float rs[2][4];
; #pragma unroll
;         for (int ai = 0; ai < 2; ++ai)
; #pragma unroll
;             for (int m = 0; m < 4; ++m) rs[ai][m] = RSS[row0 + ai * HALF + m * 16];
; #pragma unroll
;         for (int ai = 0; ai < 2; ++ai)
; #pragma unroll
;             for (int m = 0; m < 4; ++m) rs[ai][m] = rsqrtf(rs[ai][m] * (1.0f / 1024.0f) + EPS);
;         const int lane_ = fq * 16 + fr, idx1 = 4 * (fr == 0 ? lane_ + 15 : lane_ - 1), idx2 = 4 * (fr < 2 ? lane_ + 14 : lane_ - 2);
;         if (u.pm < 64) {
;     ...
;             for (int n = 0; n < 2; ++n) {
;                 const f32x4 w0 = *(const f32x4*)(cw + colt + 4 * n), w1 = *(const f32x4*)(cw + 2816 + colt + 4 * n), w2 = *(const f32x4*)(cw + 5632 + colt + 4 * n), bb = *(const f32x4*)(cb + colt + 4 * n);
; #pragma unroll
;                 for (int ai = 0; ai < 2; ++ai)
; #pragma unroll
;                     for (int m = 0; m < 4; ++m) {
;                         const int row = row0 + ai * HALF + m * 16, rl = row - MPR, bs = rl >> 2, t = rl & 3;
;                         const f32x4 a = acc[ai][0][m][n] * rs[ai][m], uu = acc[ai][1][m][n] * rs[ai][m]; f32x4 gg, s0 = {0.f, 0.f, 0.f, 0.f}, s1 = {0.f, 0.f, 0.f, 0.f};
;                         const float* sc = sconv + (size_t)bs * 2 * 2816 + colt + 4 * n;
;                         if (t == 0) s0 = *(const f32x4*)sc;
;                         if (t <= 1) s1 = *(const f32x4*)(sc + 2816);
.LBB0_895:
	s_load_dwordx4 s[20:23], s[14:15], 0x98
	s_lshl_b32 s6, s34, 8
	v_mbcnt_lo_u32_b32 v238, -1, 0
	v_mbcnt_hi_u32_b32 v238, -1, v238
	s_add_i32 s6, s6, s1
	v_and_b32_e32 v237, 15, v238
	v_or_b32_e32 v192, s6, v237
	v_ashrrev_i32_e32 v193, 31, v192
	v_lshl_add_u64 v[130:131], v[192:193], 2, s[44:45]
	global_load_dword v134, v[130:131], off
	global_load_dword v137, v[130:131], off offset:576
	global_load_dword v138, v[130:131], off offset:640
	v_or_b32_e32 v190, 16, v192
	v_ashrrev_i32_e32 v191, 31, v190
	v_lshl_add_u64 v[132:133], v[190:191], 2, s[44:45]
	global_load_dword v135, v[132:133], off
	v_or_b32_e32 v188, 32, v192
	v_ashrrev_i32_e32 v189, 31, v188
	v_lshl_add_u64 v[132:133], v[188:189], 2, s[44:45]
	global_load_dword v136, v[132:133], off
	v_or_b32_e32 v186, 48, v192
	v_ashrrev_i32_e32 v187, 31, v186
	v_lshl_add_u64 v[132:133], v[186:187], 2, s[44:45]
	global_load_dword v132, v[132:133], off
	s_lshl_b32 s6, s30, 7
	global_load_dword v133, v[130:131], off offset:512
	v_ashrrev_i32_e32 v239, 4, v238
	global_load_dword v130, v[130:131], off offset:704
	s_or_b32 s6, s6, s0
	v_lshl_add_u32 v168, v239, 3, s6
	v_add_u32_e32 v189, 0x80, v192
	v_add_u32_e32 v191, 0x90, v192
	v_add_u32_e32 v193, 0xa0, v192
	v_add_u32_e32 v187, 0xb0, v192
	s_cmp_lt_i32 s34, 64
	v_ashrrev_i32_e32 v169, 31, v168
	s_waitcnt vmcnt(0)
	v_fmamk_f32 v131, v134, 0x3a800000, v234
	v_cmp_gt_f32_e32 vcc, s3, v131
	v_mul_f32_e32 v134, 0x4b800000, v131
	v_fmamk_f32 v130, v130, 0x3a800000, v234
	v_cndmask_b32_e32 v131, v131, v134, vcc
	v_rsq_f32_e32 v131, v131
	s_nop 0
	v_mul_f32_e32 v134, 0x45800000, v131
	v_cndmask_b32_e32 v184, v131, v134, vcc
	v_fmamk_f32 v131, v135, 0x3a800000, v234
	v_cmp_gt_f32_e32 vcc, s3, v131
	v_mul_f32_e32 v134, 0x4b800000, v131
	s_nop 0
	v_cndmask_b32_e32 v131, v131, v134, vcc
	v_rsq_f32_e32 v131, v131
	s_nop 0
	v_mul_f32_e32 v134, 0x45800000, v131
	v_cndmask_b32_e32 v182, v131, v134, vcc
	v_fmamk_f32 v131, v136, 0x3a800000, v234
	v_cmp_gt_f32_e32 vcc, s3, v131
	v_mul_f32_e32 v134, 0x4b800000, v131
	s_nop 0
	v_cndmask_b32_e32 v131, v131, v134, vcc
	v_rsq_f32_e32 v131, v131
	s_nop 0
	v_mul_f32_e32 v134, 0x45800000, v131
	v_cndmask_b32_e32 v180, v131, v134, vcc
	v_fmamk_f32 v131, v132, 0x3a800000, v234
	v_cmp_gt_f32_e32 vcc, s3, v131
	v_mul_f32_e32 v132, 0x4b800000, v131
	s_nop 0
	v_cndmask_b32_e32 v131, v131, v132, vcc
	v_rsq_f32_e32 v131, v131
	s_nop 0
	v_mul_f32_e32 v132, 0x45800000, v131
	v_cndmask_b32_e32 v178, v131, v132, vcc
	v_fmamk_f32 v131, v133, 0x3a800000, v234
	v_cmp_gt_f32_e32 vcc, s3, v131
	v_mul_f32_e32 v132, 0x4b800000, v131
	s_nop 0
	v_cndmask_b32_e32 v131, v131, v132, vcc
	v_rsq_f32_e32 v131, v131
	s_nop 0
	v_mul_f32_e32 v132, 0x45800000, v131
	v_cndmask_b32_e32 v176, v131, v132, vcc
	v_fmamk_f32 v131, v137, 0x3a800000, v234
	v_cmp_gt_f32_e32 vcc, s3, v131
	v_mul_f32_e32 v132, 0x4b800000, v131
	s_nop 0
	v_cndmask_b32_e32 v131, v131, v132, vcc
	v_rsq_f32_e32 v131, v131
	s_nop 0
	v_mul_f32_e32 v132, 0x45800000, v131
	v_cndmask_b32_e32 v174, v131, v132, vcc
	v_fmamk_f32 v131, v138, 0x3a800000, v234
	v_cmp_gt_f32_e32 vcc, s3, v131
	v_mul_f32_e32 v132, 0x4b800000, v131
	s_nop 0
	v_cndmask_b32_e32 v131, v131, v132, vcc
	v_rsq_f32_e32 v131, v131
	s_nop 0
	v_mul_f32_e32 v132, 0x45800000, v131
	v_cndmask_b32_e32 v172, v131, v132, vcc
	v_cmp_gt_f32_e32 vcc, s3, v130
	v_mul_f32_e32 v131, 0x4b800000, v130
	s_nop 0
	v_cndmask_b32_e32 v130, v130, v131, vcc
	v_rsq_f32_e32 v130, v130
	s_nop 0
	v_mul_f32_e32 v131, 0x45800000, v130
	v_cndmask_b32_e32 v170, v130, v131, vcc
	s_cbranch_scc1 .LBB0_993
	s_load_dwordx4 s[8:11], s[14:15], 0x98
	v_lshlrev_b64 v[146:147], 2, v[168:169]
	v_lshl_add_u64 v[134:135], s[72:73], 0, v[146:147]
	v_lshl_add_u64 v[138:139], s[74:75], 0, v[146:147]
	v_add_u32_e32 v148, 0xffffc000, v192
	s_waitcnt lgkmcnt(0)
	v_lshl_add_u64 v[202:203], s[8:9], 0, v[146:147]
	v_lshl_add_u64 v[206:207], s[10:11], 0, v[146:147]
	global_load_dwordx4 v[130:133], v[202:203], off
	s_nop 0
	global_load_dwordx4 v[134:137], v[134:135], off
	s_nop 0
	global_load_dwordx4 v[138:141], v[138:139], off
	v_ashrrev_i32_e32 v171, 2, v148
	global_load_dwordx4 v[142:145], v[206:207], off
	v_mov_b64_e32 v[148:149], s[26:27]
	v_and_b32_e32 v156, 3, v238
	v_mad_i64_i32 v[148:149], s[8:9], v171, s46, v[148:149]
	v_cmp_eq_u32_e64 s[6:7], 0, v156
	v_lshl_add_u64 v[194:195], v[148:149], 0, v[146:147]
	v_mov_b32_e32 v150, 0
	v_mov_b32_e32 v146, 0
	v_mov_b32_e32 v147, 0
	v_mov_b32_e32 v148, 0
	v_mov_b32_e32 v149, 0
	s_and_saveexec_b64 s[8:9], s[6:7]
	s_cbranch_execz .LBB0_898
	global_load_dwordx4 v[146:149], v[194:195], off

; #define PG8_LAS __attribute__((address_space(3)))
; __device__ __forceinline__ float sigm(float x) { return __builtin_amdgcn_rcpf(1.0f + __builtin_amdgcn_exp2f(-x * LOG2E)); }
;     __device__ __forceinline__ void operator()(const f32x4 (&acc)[2][2][4][2], const Unit& u, int wr, int wc, int fr, int fq) const {
;     ...
;             if (fr >= 14) {
; #pragma unroll
;                 for (int ai = 0; ai < 2; ++ai)
; #pragma unroll
;                     for (int n = 0; n < 2; ++n) *(PG8_LAS f32x4*)(xch + (((wr * 4 + wc) * 8 + (fr - 14) * 4 + fq) * 16 + ai * 8 + n * 4)) = acc[ai][0][3][n] * rs[ai][3];
;             }
;             asm volatile("s_waitcnt lgkmcnt(0)" ::: "memory"); __builtin_amdgcn_s_barrier(); asm volatile("" ::: "memory");
; #pragma unroll
;             for (int n = 0; n < 2; ++n) {
;                 const f32x4 w0 = *(const f32x4*)(cw + colt + 4 * n), w1 = *(const f32x4*)(cw + 2816 + colt + 4 * n), w2 = *(const f32x4*)(cw + 5632 + colt + 4 * n), bb = *(const f32x4*)(cb + colt + 4 * n);
; #pragma unroll
;                 for (int ai = 0; ai < 2; ++ai) {
;                     f32x4 prevA = {0.f, 0.f, 0.f, 0.f};
;                     const bool has_prev = (wr == 1) || (ai == 1);
;     ...
;                     if (has_prev && fr >= 14) { const int pw = (wr == 1 ? 0 : 4) + wc, pai = (wr == 1) ? ai : 0; prevA = *(const PG8_LAS f32x4*)(xch + ((pw * 8 + (fr - 14) * 4 + fq) * 16 + pai * 8 + n * 4)); }
;     ...
; #pragma unroll
;                     for (int m = 0; m < 4; ++m) {
;                         const int row = row0 + ai * HALF + m * 16;
;                         const f32x4 a = acc[ai][0][m][n] * rs[ai][m], uu = acc[ai][1][m][n] * rs[ai][m]; f32x4 gg;
; #pragma unroll
;                         for (int j = 0; j < 4; ++j) {
;                             const float p1 = __builtin_bit_cast(float, __builtin_amdgcn_ds_bpermute(idx1, __builtin_bit_cast(int, fr == 15 ? prevA[j] : a[j])));
;                             const float p2 = __builtin_bit_cast(float, __builtin_amdgcn_ds_bpermute(idx2, __builtin_bit_cast(int, fr >= 14 ? prevA[j] : a[j])));
;                             const float c = bb[j] + w0[j] * p2 + w1[j] * p1 + w2[j] * a[j];
;                             gg[j] = c * sigm(c) * uu[j];
;                         }
;                         *(u32x2*)(G + (size_t)row * 2816 + colt + 4 * n) = (u32x2){cvt_pk_bf16(gg[0], gg[1]), cvt_pk_bf16(gg[2], gg[3])};
.LBB0_994:
	v_lshlrev_b64 v[194:195], 2, v[168:169]
	v_lshl_add_u64 v[134:135], s[72:73], 0, v[194:195]
	v_lshl_add_u64 v[138:139], s[74:75], 0, v[194:195]
	s_waitcnt lgkmcnt(0)
	v_lshl_add_u64 v[196:197], s[20:21], 0, v[194:195]
	v_lshl_add_u64 v[198:199], s[22:23], 0, v[194:195]
	global_load_dwordx4 v[130:133], v[196:197], off
	s_nop 0
	global_load_dwordx4 v[134:137], v[134:135], off
	s_nop 0
	global_load_dwordx4 v[138:141], v[138:139], off
	v_lshlrev_b32_e32 v171, 6, v239
	global_load_dwordx4 v[142:145], v[198:199], off
	v_add_co_u32_e32 v248, vcc, 0x2000, v196
	global_load_dwordx4 v[218:221], v[196:197], off offset:16
	s_nop 0
	v_addc_co_u32_e32 v249, vcc, 0, v197, vcc
	v_add_co_u32_e32 v250, vcc, 0x5000, v196
	s_nop 1
	v_addc_co_u32_e32 v251, vcc, 0, v197, vcc
	global_load_dwordx4 v[222:225], v[248:249], off offset:3088
	global_load_dwordx4 v[226:229], v[250:251], off offset:2064
	global_load_dwordx4 v[244:247], v[198:199], off offset:16
	v_cmp_lt_u32_e64 s[6:7], 13, v237
	v_cmp_gt_u32_e32 vcc, 14, v237
	v_lshlrev_b32_e32 v146, 8, v237
	s_and_saveexec_b64 s[8:9], vcc
	s_xor_b64 s[8:9], exec, s[8:9]
	v_lshlrev_b32_e32 v146, 8, v237
	s_andn2_saveexec_b64 s[8:9], s[8:9]
	s_cbranch_execz .LBB0_998
	v_readlane_b32 s12, v255, 24
	v_pk_mul_f32 v[250:251], v[104:105], v[178:179] op_sel_hi:[1,0]
	v_pk_mul_f32 v[248:249], v[102:103], v[178:179] op_sel_hi:[1,0]
	v_add_lshl_u32 v252, s12, v239, 6
	s_add_i32 s12, 0, 0x20a80
	v_add3_u32 v252, s12, v146, v252
	ds_write_b128 v252, v[248:251]
	v_pk_mul_f32 v[250:251], v[100:101], v[178:179] op_sel_hi:[1,0]
	v_pk_mul_f32 v[248:249], v[98:99], v[178:179] op_sel_hi:[1,0]
	ds_write_b128 v252, v[248:251] offset:16
	v_pk_mul_f32 v[250:251], v[40:41], v[170:171] op_sel_hi:[1,0]
	v_pk_mul_f32 v[248:249], v[38:39], v[170:171] op_sel_hi:[1,0]
	ds_write_b128 v252, v[248:251] offset:32
	v_pk_mul_f32 v[250:251], v[36:37], v[170:171] op_sel_hi:[1,0]
	v_pk_mul_f32 v[248:249], v[34:35], v[170:171] op_sel_hi:[1,0]
	ds_write_b128 v252, v[248:251] offset:48
.LBB0_998:
	s_or_b64 exec, exec, s[8:9]
	s_waitcnt lgkmcnt(0)
	s_barrier
	v_readlane_b32 s8, v255, 25
	s_and_b64 s[12:13], s[40:41], s[6:7]
	v_mov_b32_e32 v154, 0
	v_add_u32_e32 v173, s8, v146
	v_mov_b32_e32 v155, 0
	v_mov_b32_e32 v156, 0
	v_mov_b32_e32 v157, 0
	s_and_saveexec_b64 s[8:9], s[12:13]
	s_movk_i32 s20, 0xf200
	v_add3_u32 v146, v173, v171, s20
	ds_read_b128 v[154:157], v146
	s_or_b64 exec, exec, s[8:9]
	v_cmp_eq_u32_e32 vcc, 0, v237
	v_cmp_eq_u32_e64 s[8:9], 15, v237
	v_pk_mul_f32 v[148:149], v[128:129], v[184:185] op_sel_hi:[1,0]
	v_cndmask_b32_e64 v146, -1, 15, vcc
	v_cmp_gt_u32_e32 vcc, 2, v237
	v_add_lshl_u32 v209, v146, v238, 2
	v_pk_mul_f32 v[152:153], v[96:97], v[184:185] op_sel_hi:[1,0]
	v_cndmask_b32_e64 v146, -2, 14, vcc
	v_add_lshl_u32 v208, v146, v238, 2
	v_pk_mul_f32 v[146:147], v[126:127], v[184:185] op_sel_hi:[1,0]
	v_pk_mul_f32 v[150:151], v[94:95], v[184:185] op_sel_hi:[1,0]
	s_waitcnt lgkmcnt(0)
	v_cndmask_b32_e64 v175, v146, v154, s[8:9]
	s_nop 1
	v_mov_b32_dpp v200, v175 row_ror:1 row_mask:0xf bank_mask:0xf
	v_cndmask_b32_e64 v154, v146, v154, s[6:7]
	v_cndmask_b32_e64 v175, v147, v155, s[8:9]
	v_cndmask_b32_e64 v155, v147, v155, s[6:7]
	v_mov_b32_dpp v154, v154 row_ror:2 row_mask:0xf bank_mask:0xf
	s_nop 1
	v_mov_b32_dpp v155, v155 row_ror:2 row_mask:0xf bank_mask:0xf
	v_mov_b32_dpp v201, v175 row_ror:1 row_mask:0xf bank_mask:0xf
	s_and_b64 s[88:89], s[70:71], vcc
	s_waitcnt vmcnt(0) lgkmcnt(1)
	v_pk_fma_f32 v[154:155], v[130:131], v[154:155], v[142:143]
	s_waitcnt lgkmcnt(0)
	v_pk_fma_f32 v[154:155], v[134:135], v[200:201], v[154:155]
	s_nop 0
	v_pk_fma_f32 v[154:155], v[146:147], v[138:139], v[154:155]
	s_nop 0
	v_mul_f32_e32 v175, 0xbfb8aa3b, v154
	v_exp_f32_e32 v175, v175
	s_nop 0
	v_add_f32_e32 v175, 1.0, v175
	v_rcp_f32_e32 v200, v175
	v_mul_f32_e32 v175, 0xbfb8aa3b, v155
	v_exp_f32_e32 v175, v175
	s_nop 0
	v_add_f32_e32 v175, 1.0, v175
	v_rcp_f32_e32 v201, v175
	v_cndmask_b32_e64 v175, v148, v156, s[8:9]
	v_cndmask_b32_e64 v156, v148, v156, s[6:7]
	s_nop 1
	v_mov_b32_dpp v156, v156 row_ror:2 row_mask:0xf bank_mask:0xf
	v_pk_mul_f32 v[154:155], v[154:155], v[200:201]
	v_mov_b32_dpp v200, v175 row_ror:1 row_mask:0xf bank_mask:0xf
	v_cndmask_b32_e64 v175, v149, v157, s[8:9]
	v_cndmask_b32_e64 v157, v149, v157, s[6:7]
	s_nop 1
	v_mov_b32_dpp v157, v157 row_ror:2 row_mask:0xf bank_mask:0xf
	v_mov_b32_dpp v201, v175 row_ror:1 row_mask:0xf bank_mask:0xf
	v_pk_mul_f32 v[154:155], v[150:151], v[154:155]
	s_waitcnt lgkmcnt(1)
	v_pk_fma_f32 v[156:157], v[132:133], v[156:157], v[144:145]
	s_waitcnt lgkmcnt(0)
	v_pk_fma_f32 v[156:157], v[136:137], v[200:201], v[156:157]
	v_cvt_pk_bf16_f32 v154, v154, v155
	v_pk_fma_f32 v[156:157], v[148:149], v[140:141], v[156:157]
	s_nop 0
	v_mul_f32_e32 v175, 0xbfb8aa3b, v156
	v_exp_f32_e32 v175, v175
	s_nop 0
	v_add_f32_e32 v175, 1.0, v175
	v_rcp_f32_e32 v200, v175
	v_mul_f32_e32 v175, 0xbfb8aa3b, v157
	v_exp_f32_e32 v175, v175
	s_nop 0
	v_add_f32_e32 v175, 1.0, v175
	v_rcp_f32_e32 v201, v175
	v_lshl_or_b32 v175, s34, 1, v237
	v_pk_mul_f32 v[156:157], v[156:157], v[200:201]
	s_nop 0
	v_pk_mul_f32 v[156:157], v[152:153], v[156:157]
	s_nop 0
	v_cvt_pk_bf16_f32 v155, v156, v157
	v_mov_b64_e32 v[156:157], s[42:43]
	v_mad_i64_i32 v[156:157], s[20:21], v192, s47, v[156:157]
	v_lshl_add_u64 v[206:207], v[168:169], 1, v[156:157]
	global_store_dwordx2 v[206:207], v[154:155], off
	s_and_saveexec_b64 s[90:91], s[88:89]
	s_cbranch_execz .LBB0_1002
	v_readlane_b32 s20, v255, 16
	v_readlane_b32 s21, v255, 17
	s_nop 1
	v_mov_b64_e32 v[154:155], s[20:21]
	v_mad_i64_i32 v[154:155], s[20:21], v175, s48, v[154:155]
	v_readlane_b32 s20, v255, 18
	v_lshl_add_u64 v[154:155], v[154:155], 0, v[194:195]
	v_readlane_b32 s21, v255, 19
	global_store_dwordx4 v[154:155], v[146:149], off
	s_nop 0
	v_mov_b64_e32 v[154:155], s[20:21]
	v_mad_i64_i32 v[154:155], s[20:21], v175, s48, v[154:155]
	v_lshl_add_u64 v[154:155], v[154:155], 0, v[194:195]
	global_store_dwordx4 v[154:155], v[150:153], off
